# P4 rstd LDS reads software-pipelined; accumulator zeroing with 64-bit moves
# speedup vs baseline: 1.0038x; 1.0002x over previous
; template <class Epi, class Sched, bool ALIGN_EPI = false, bool SP2 = false>
; __device__ __forceinline__ void gemm_phase(PG8_LAS unsigned char* lds, const Gemm g, const Sched& S, const Epi& E) {
;     ...
;         for (int a = 0; a < 2; ++a)
; #pragma unroll
;             for (int b = 0; b < 2; ++b)
; #pragma unroll
;                 for (int m = 0; m < 4; ++m)
; #pragma unroll
;                     for (int n = 0; n < 2; ++n) acc[a][b][m][n] = (f32x4){0.f, 0.f, 0.f, 0.f};
;         cur = nxt; cA = nA; cB = nB; ++ui;
.LBB0_207:
	s_ashr_i32 s15, s14, 31
	s_lshl_b64 s[16:17], s[14:15], 19
	s_add_u32 s16, s28, s16
	s_addc_u32 s17, s29, s17
	s_and_b64 s[18:19], s[0:1], exec
	s_cselect_b32 s15, s17, s23
	s_cselect_b32 s50, s16, s22
	s_ashr_i32 s13, s12, 31
	s_lshl_b64 s[18:19], s[12:13], 19
	s_add_u32 s18, s30, s18
	s_addc_u32 s19, s31, s19
	s_and_b64 s[26:27], s[0:1], exec
	s_cselect_b32 s13, s19, s25
	s_cselect_b32 s51, s18, s24
	s_add_u32 s22, s22, 0x40080
	s_addc_u32 s23, s23, 0
	s_add_u32 s52, s24, 0x100
	s_addc_u32 s53, s25, 0
	s_mov_b32 s54, -2
	v_mov_b64_e32 v[2:3], 0
	v_mov_b64_e32 v[4:5], 0
	v_mov_b64_e32 v[6:7], 0
	v_mov_b64_e32 v[8:9], 0
	v_mov_b64_e32 v[10:11], 0
	v_mov_b64_e32 v[12:13], 0
	v_mov_b64_e32 v[14:15], 0
	v_mov_b64_e32 v[16:17], 0
	v_mov_b64_e32 v[18:19], 0
	v_mov_b64_e32 v[20:21], 0
	v_mov_b64_e32 v[22:23], 0
	v_mov_b64_e32 v[24:25], 0
	v_mov_b64_e32 v[26:27], 0
	v_mov_b64_e32 v[28:29], 0
	v_mov_b64_e32 v[30:31], 0
	v_mov_b64_e32 v[32:33], 0
	v_mov_b64_e32 v[34:35], 0
	v_mov_b64_e32 v[36:37], 0
	v_mov_b64_e32 v[38:39], 0
	v_mov_b64_e32 v[40:41], 0
	v_mov_b64_e32 v[42:43], 0
	v_mov_b64_e32 v[44:45], 0
	v_mov_b64_e32 v[46:47], 0
	v_mov_b64_e32 v[48:49], 0
	v_mov_b64_e32 v[50:51], 0
	v_mov_b64_e32 v[52:53], 0
	v_mov_b64_e32 v[54:55], 0
	v_mov_b64_e32 v[56:57], 0
	v_mov_b64_e32 v[58:59], 0
	v_mov_b64_e32 v[60:61], 0
	v_mov_b64_e32 v[62:63], 0
	v_mov_b64_e32 v[64:65], 0
	v_mov_b64_e32 v[66:67], 0
	v_mov_b64_e32 v[68:69], 0
	v_mov_b64_e32 v[70:71], 0
	v_mov_b64_e32 v[72:73], 0
	v_mov_b64_e32 v[74:75], 0
	v_mov_b64_e32 v[76:77], 0
	v_mov_b64_e32 v[78:79], 0
	v_mov_b64_e32 v[80:81], 0
	v_mov_b64_e32 v[82:83], 0
	v_mov_b64_e32 v[84:85], 0
	v_mov_b64_e32 v[86:87], 0
	v_mov_b64_e32 v[88:89], 0
	v_mov_b64_e32 v[90:91], 0
	v_mov_b64_e32 v[92:93], 0
	v_mov_b64_e32 v[94:95], 0
	v_mov_b64_e32 v[96:97], 0
	v_mov_b64_e32 v[98:99], 0
	v_mov_b64_e32 v[100:101], 0
	v_mov_b64_e32 v[102:103], 0
	v_mov_b64_e32 v[104:105], 0
	v_mov_b64_e32 v[106:107], 0
	v_mov_b64_e32 v[108:109], 0
	v_mov_b64_e32 v[110:111], 0
	v_mov_b64_e32 v[112:113], 0
	v_mov_b64_e32 v[114:115], 0
	v_mov_b64_e32 v[116:117], 0
	v_mov_b64_e32 v[118:119], 0
	v_mov_b64_e32 v[120:121], 0
	v_mov_b64_e32 v[122:123], 0
	v_mov_b64_e32 v[124:125], 0
	v_mov_b64_e32 v[126:127], 0
	v_mov_b64_e32 v[128:129], 0

; template <class Epi, class Sched, bool ALIGN_EPI = false, bool SP2 = false>
; __device__ __forceinline__ void gemm_phase(PG8_LAS unsigned char* lds, const Gemm g, const Sched& S, const Epi& E) {
;     ...
;         for (int a = 0; a < 2; ++a)
; #pragma unroll
;             for (int b = 0; b < 2; ++b)
; #pragma unroll
;                 for (int m = 0; m < 4; ++m)
; #pragma unroll
;                     for (int n = 0; n < 2; ++n) acc[a][b][m][n] = (f32x4){0.f, 0.f, 0.f, 0.f};
;         cur = nxt; cA = nA; cB = nB; ++ui;
.LBB0_288:
	s_add_u32 s39, s6, 0x100
	s_addc_u32 s40, s7, 0
	s_mov_b32 s41, -2
	v_mov_b64_e32 v[2:3], 0
	v_mov_b64_e32 v[4:5], 0
	v_mov_b64_e32 v[6:7], 0
	v_mov_b64_e32 v[8:9], 0
	v_mov_b64_e32 v[10:11], 0
	v_mov_b64_e32 v[12:13], 0
	v_mov_b64_e32 v[14:15], 0
	v_mov_b64_e32 v[16:17], 0
	v_mov_b64_e32 v[18:19], 0
	v_mov_b64_e32 v[20:21], 0
	v_mov_b64_e32 v[22:23], 0
	v_mov_b64_e32 v[24:25], 0
	v_mov_b64_e32 v[26:27], 0
	v_mov_b64_e32 v[28:29], 0
	v_mov_b64_e32 v[30:31], 0
	v_mov_b64_e32 v[32:33], 0
	v_mov_b64_e32 v[34:35], 0
	v_mov_b64_e32 v[36:37], 0
	v_mov_b64_e32 v[38:39], 0
	v_mov_b64_e32 v[40:41], 0
	v_mov_b64_e32 v[42:43], 0
	v_mov_b64_e32 v[44:45], 0
	v_mov_b64_e32 v[46:47], 0
	v_mov_b64_e32 v[48:49], 0
	v_mov_b64_e32 v[50:51], 0
	v_mov_b64_e32 v[52:53], 0
	v_mov_b64_e32 v[54:55], 0
	v_mov_b64_e32 v[56:57], 0
	v_mov_b64_e32 v[58:59], 0
	v_mov_b64_e32 v[60:61], 0
	v_mov_b64_e32 v[62:63], 0
	v_mov_b64_e32 v[64:65], 0
	v_mov_b64_e32 v[66:67], 0
	v_mov_b64_e32 v[68:69], 0
	v_mov_b64_e32 v[70:71], 0
	v_mov_b64_e32 v[72:73], 0
	v_mov_b64_e32 v[74:75], 0
	v_mov_b64_e32 v[76:77], 0
	v_mov_b64_e32 v[78:79], 0
	v_mov_b64_e32 v[80:81], 0
	v_mov_b64_e32 v[82:83], 0
	v_mov_b64_e32 v[84:85], 0
	v_mov_b64_e32 v[86:87], 0
	v_mov_b64_e32 v[88:89], 0
	v_mov_b64_e32 v[90:91], 0
	v_mov_b64_e32 v[92:93], 0
	v_mov_b64_e32 v[94:95], 0
	v_mov_b64_e32 v[96:97], 0
	v_mov_b64_e32 v[98:99], 0
	v_mov_b64_e32 v[100:101], 0
	v_mov_b64_e32 v[102:103], 0
	v_mov_b64_e32 v[104:105], 0
	v_mov_b64_e32 v[106:107], 0
	v_mov_b64_e32 v[108:109], 0
	v_mov_b64_e32 v[110:111], 0
	v_mov_b64_e32 v[112:113], 0
	v_mov_b64_e32 v[114:115], 0
	v_mov_b64_e32 v[116:117], 0
	v_mov_b64_e32 v[118:119], 0
	v_mov_b64_e32 v[120:121], 0
	v_mov_b64_e32 v[122:123], 0
	v_mov_b64_e32 v[124:125], 0
	v_mov_b64_e32 v[126:127], 0
	v_mov_b64_e32 v[128:129], 0

; template <class Epi, class Sched, bool ALIGN_EPI = false, bool SP2 = false>
; __device__ __forceinline__ void gemm_phase(PG8_LAS unsigned char* lds, const Gemm g, const Sched& S, const Epi& E) {
;     ...
;         for (int a = 0; a < 2; ++a)
; #pragma unroll
;             for (int b = 0; b < 2; ++b)
; #pragma unroll
;                 for (int m = 0; m < 4; ++m)
; #pragma unroll
;                     for (int n = 0; n < 2; ++n) acc[a][b][m][n] = (f32x4){0.f, 0.f, 0.f, 0.f};
;         cur = nxt; cA = nA; cB = nB; ++ui;
.LBB0_437:
	s_ashr_i32 s47, s46, 31
	s_lshl_b64 s[8:9], s[46:47], 19
	s_add_u32 s48, s64, s8
	s_addc_u32 s49, s65, s9
	s_and_b64 s[8:9], s[2:3], exec
	s_cselect_b32 s7, s49, s11
	s_cselect_b32 s31, s48, s10
	s_ashr_i32 s45, s44, 31
	s_lshl_b64 s[8:9], s[44:45], 19
	s_add_u32 s50, s66, s8
	s_addc_u32 s51, s67, s9
	s_and_b64 s[8:9], s[2:3], exec
	s_cselect_b32 s45, s51, s57
	s_cselect_b32 s47, s50, s56
	s_ashr_i32 s5, s4, 31
	s_lshl_b32 s8, s6, 8
	s_lshl_b64 s[28:29], s[4:5], 14
	s_ashr_i32 s5, s4, 5
	s_ashr_i32 s9, s8, 31
	s_add_u32 s52, s14, s28
	s_mul_hi_i32 s54, s5, 0x6800
	s_mulk_i32 s5, 0x6800
	s_addc_u32 s53, s88, s29
	s_add_u32 s5, s77, s5
	s_addc_u32 s55, s78, s54
	s_lshl_b64 s[28:29], s[8:9], 2
	s_add_u32 s54, s5, s28
	s_addc_u32 s55, s55, s29
	s_add_u32 s5, s56, 0x100
	v_lshl_add_u64 v[196:197], s[10:11], 0, v[188:189]
	v_lshl_add_u64 v[198:199], s[10:11], 0, v[190:191]
	s_addc_u32 s9, s57, 0
	s_mov_b32 s28, 0
	s_mov_b64 s[56:57], 0
	v_mov_b64_e32 v[2:3], 0
	v_mov_b64_e32 v[4:5], 0
	v_mov_b64_e32 v[6:7], 0
	v_mov_b64_e32 v[8:9], 0
	v_mov_b64_e32 v[10:11], 0
	v_mov_b64_e32 v[12:13], 0
	v_mov_b64_e32 v[14:15], 0
	v_mov_b64_e32 v[16:17], 0
	v_mov_b64_e32 v[18:19], 0
	v_mov_b64_e32 v[20:21], 0
	v_mov_b64_e32 v[22:23], 0
	v_mov_b64_e32 v[24:25], 0
	v_mov_b64_e32 v[26:27], 0
	v_mov_b64_e32 v[28:29], 0
	v_mov_b64_e32 v[30:31], 0
	v_mov_b64_e32 v[32:33], 0
	v_mov_b64_e32 v[34:35], 0
	v_mov_b64_e32 v[36:37], 0
	v_mov_b64_e32 v[38:39], 0
	v_mov_b64_e32 v[40:41], 0
	v_mov_b64_e32 v[58:59], 0
	v_mov_b64_e32 v[60:61], 0
	v_mov_b64_e32 v[62:63], 0
	v_mov_b64_e32 v[64:65], 0
	v_mov_b64_e32 v[66:67], 0
	v_mov_b64_e32 v[68:69], 0
	v_mov_b64_e32 v[70:71], 0
	v_mov_b64_e32 v[72:73], 0
	v_mov_b64_e32 v[74:75], 0
	v_mov_b64_e32 v[76:77], 0
	v_mov_b64_e32 v[78:79], 0
	v_mov_b64_e32 v[80:81], 0
	v_mov_b64_e32 v[82:83], 0
	v_mov_b64_e32 v[84:85], 0
	v_mov_b64_e32 v[86:87], 0
	v_mov_b64_e32 v[88:89], 0
	v_mov_b64_e32 v[90:91], 0
	v_mov_b64_e32 v[92:93], 0
	v_mov_b64_e32 v[94:95], 0
	v_mov_b64_e32 v[96:97], 0
	v_mov_b64_e32 v[98:99], 0
	v_mov_b64_e32 v[100:101], 0
	v_mov_b64_e32 v[102:103], 0
	v_mov_b64_e32 v[104:105], 0
	v_mov_b64_e32 v[106:107], 0
	v_mov_b64_e32 v[108:109], 0
	v_mov_b64_e32 v[110:111], 0
	v_mov_b64_e32 v[112:113], 0
	v_mov_b64_e32 v[114:115], 0
	v_mov_b64_e32 v[116:117], 0
	v_mov_b64_e32 v[118:119], 0
	v_mov_b64_e32 v[120:121], 0
	v_mov_b64_e32 v[122:123], 0
	v_mov_b64_e32 v[124:125], 0
	v_mov_b64_e32 v[126:127], 0
	v_mov_b64_e32 v[128:129], 0
	v_mov_b64_e32 v[130:131], 0
	v_mov_b64_e32 v[132:133], 0
	v_mov_b64_e32 v[134:135], 0
	v_mov_b64_e32 v[136:137], 0
	v_mov_b64_e32 v[138:139], 0
	v_mov_b64_e32 v[140:141], 0
	v_mov_b64_e32 v[142:143], 0
	v_mov_b64_e32 v[144:145], 0
	s_branch .LBB0_439

; #define PG8_LAS __attribute__((address_space(3)))
; #define EPI_ROWS _Pragma("unroll") for (int ai = 0; ai < 2; ++ai) _Pragma("unroll") for (int m = 0; m < 4; ++m)
; __device__ __forceinline__ float rstd_lds(const PG8_LAS unsigned char* scr, int lrow) {
;     const PG8_LAS f32x4* p = (const PG8_LAS f32x4*)(scr + lrow * 64);
;     const f32x4 s = (p[0] + p[1]) + (p[2] + p[3]);
;     return __builtin_amdgcn_rsqf(((s[0] + s[1]) + (s[2] + s[3])) * (1.0f / DM) + RMS_EPS);
; }
;     __device__ __forceinline__ void operator()(const f32x4 (&acc)[2][2][4][2], const Unit& u, int wr, int wc, int fr, int fq) const {
;     ...
;         EPI_ROWS { rsv[ai][m] = rstd_lds(scr, EPI_LROW); asm volatile("" : "+v"(rsv[ai][m]) :: "memory"); }
.LBB0_462:
	v_lshlrev_b32_e32 v165, 6, v175
	v_add_u32_e32 v146, s89, v165
	ds_read_b128 v[148:151], v146
	ds_read_b128 v[152:155], v146 offset:16
	ds_read_b128 v[156:159], v146 offset:32
	ds_read_b128 v[160:163], v146 offset:48
	v_lshlrev_b32_e32 v197, 4, v147
	v_add_u32_e32 v147, v197, v175
	v_add_u32_e32 v228, s90, v165
	ds_read_b128 v[230:233], v228
	ds_read_b128 v[234:237], v228 offset:16
	ds_read_b128 v[238:241], v228 offset:32
	ds_read_b128 v[242:245], v228 offset:48
	s_waitcnt lgkmcnt(4)
	v_pk_add_f32 v[150:151], v[150:151], v[154:155]
	v_pk_add_f32 v[148:149], v[148:149], v[152:153]
	v_pk_add_f32 v[152:153], v[158:159], v[162:163]
	v_pk_add_f32 v[154:155], v[156:157], v[160:161]
	v_pk_add_f32 v[150:151], v[150:151], v[152:153]
	v_pk_add_f32 v[148:149], v[148:149], v[154:155]
	v_pk_mov_b32 v[152:153], v[148:149], v[150:151] op_sel:[1,0]
	v_mov_b32_e32 v149, v151
	v_pk_add_f32 v[148:149], v[152:153], v[148:149]
	v_lshlrev_b32_e32 v177, 4, v147
	v_add_f32_e32 v146, v148, v149
	v_fmamk_f32 v146, v146, 0x3a800000, v211
	v_rsq_f32_e32 v146, v146
	v_ashrrev_i32_e32 v147, 3, v147
	s_lshl_b32 s31, s4, 8
	v_add_u32_e32 v228, s91, v165
	ds_read_b128 v[148:151], v228
	ds_read_b128 v[152:155], v228 offset:16
	ds_read_b128 v[156:159], v228 offset:32
	ds_read_b128 v[160:163], v228 offset:48
	s_waitcnt lgkmcnt(4)
	v_pk_add_f32 v[232:233], v[232:233], v[236:237]
	v_pk_add_f32 v[230:231], v[230:231], v[234:235]
	v_pk_add_f32 v[234:235], v[240:241], v[244:245]
	v_pk_add_f32 v[236:237], v[238:239], v[242:243]
	v_pk_add_f32 v[232:233], v[232:233], v[234:235]
	v_pk_add_f32 v[230:231], v[230:231], v[236:237]
	v_add_f32_e32 v230, v230, v231
	v_add_f32_e32 v231, v232, v233
	v_add_f32_e32 v230, v230, v231
	v_fmamk_f32 v230, v230, 0x3a800000, v211
	v_rsq_f32_e32 v206, v230
	v_mad_u64_u32 v[172:173], s[4:5], s52, v147, 0
	v_add_u32_e32 v228, s92, v165
	ds_read_b128 v[230:233], v228
	ds_read_b128 v[234:237], v228 offset:16
	ds_read_b128 v[238:241], v228 offset:32
	ds_read_b128 v[242:245], v228 offset:48
	s_waitcnt lgkmcnt(4)
	v_pk_add_f32 v[150:151], v[150:151], v[154:155]
	v_pk_add_f32 v[148:149], v[148:149], v[152:153]
	v_pk_add_f32 v[152:153], v[158:159], v[162:163]
	v_pk_add_f32 v[154:155], v[156:157], v[160:161]
	v_pk_add_f32 v[150:151], v[150:151], v[152:153]
	v_pk_add_f32 v[148:149], v[148:149], v[154:155]
	v_add_f32_e32 v148, v148, v149
	v_add_f32_e32 v149, v150, v151
	v_add_f32_e32 v148, v148, v149
	v_fmamk_f32 v148, v148, 0x3a800000, v211
	v_rsq_f32_e32 v202, v148
	s_add_i32 s8, s84, s8
	s_ashr_i32 s9, s8, 31
	v_add_u32_e32 v228, s93, v165
	ds_read_b128 v[148:151], v228
	ds_read_b128 v[152:155], v228 offset:16
	ds_read_b128 v[156:159], v228 offset:32
	ds_read_b128 v[160:163], v228 offset:48
	s_waitcnt lgkmcnt(4)
	v_pk_add_f32 v[232:233], v[232:233], v[236:237]
	v_pk_add_f32 v[230:231], v[230:231], v[234:235]
	v_pk_add_f32 v[234:235], v[240:241], v[244:245]
	v_pk_add_f32 v[236:237], v[238:239], v[242:243]
	v_pk_add_f32 v[232:233], v[232:233], v[234:235]
	v_pk_add_f32 v[230:231], v[230:231], v[236:237]
	v_add_f32_e32 v230, v230, v231
	v_add_f32_e32 v231, v232, v233
	v_add_f32_e32 v230, v230, v231
	v_fmamk_f32 v230, v230, 0x3a800000, v211
	v_rsq_f32_e32 v200, v230
	s_xor_b64 s[56:57], s[56:57], -1
	s_add_i32 s31, s31, s79
	v_add_u32_e32 v228, s94, v165
	ds_read_b128 v[230:233], v228
	ds_read_b128 v[234:237], v228 offset:16
	ds_read_b128 v[238:241], v228 offset:32
	ds_read_b128 v[242:245], v228 offset:48
	s_waitcnt lgkmcnt(4)
	v_pk_add_f32 v[150:151], v[150:151], v[154:155]
	v_pk_add_f32 v[148:149], v[148:149], v[152:153]
	v_pk_add_f32 v[152:153], v[158:159], v[162:163]
	v_pk_add_f32 v[154:155], v[156:157], v[160:161]
	v_pk_add_f32 v[150:151], v[150:151], v[152:153]
	v_pk_add_f32 v[148:149], v[148:149], v[154:155]
	v_add_f32_e32 v148, v148, v149
	v_add_f32_e32 v149, v150, v151
	v_add_f32_e32 v148, v148, v149
	v_fmamk_f32 v148, v148, 0x3a800000, v211
	v_rsq_f32_e32 v198, v148
	s_mov_b64 s[60:61], -1
	s_xor_b64 s[58:59], s[58:59], -1
	v_add_u32_e32 v228, s95, v165
	ds_read_b128 v[148:151], v228
	ds_read_b128 v[152:155], v228 offset:16
	ds_read_b128 v[156:159], v228 offset:32
	ds_read_b128 v[160:163], v228 offset:48
	s_waitcnt lgkmcnt(4)
	v_pk_add_f32 v[232:233], v[232:233], v[236:237]
	v_pk_add_f32 v[230:231], v[230:231], v[234:235]
	v_pk_add_f32 v[234:235], v[240:241], v[244:245]
	v_pk_add_f32 v[236:237], v[238:239], v[242:243]
	v_pk_add_f32 v[232:233], v[232:233], v[234:235]
	v_pk_add_f32 v[230:231], v[230:231], v[236:237]
	v_add_f32_e32 v230, v230, v231
	v_add_f32_e32 v231, v232, v233
	v_add_f32_e32 v230, v230, v231
	v_fmamk_f32 v230, v230, 0x3a800000, v211
	v_rsq_f32_e32 v196, v230
	v_cmp_gt_u32_e64 s[6:7], 8, v175
	v_add_u32_e32 v212, s31, v175
	v_add_u32_e32 v228, s96, v165
	ds_read_b128 v[230:233], v228
	ds_read_b128 v[234:237], v228 offset:16
	ds_read_b128 v[238:241], v228 offset:32
	ds_read_b128 v[242:245], v228 offset:48
	s_waitcnt lgkmcnt(4)
; __device__ __forceinline__ u32x4 pack8(const f32x4 a, const f32x4 b) { u32x4 w; w.x = cvt_pk_bf16(a[0], a[1]); w.y = cvt_pk_bf16(a[2], a[3]); w.z = cvt_pk_bf16(b[0], b[1]); w.w = cvt_pk_bf16(b[2], b[3]); return w; }
; #define EPI_ROWS _Pragma("unroll") for (int ai = 0; ai < 2; ++ai) _Pragma("unroll") for (int m = 0; m < 4; ++m)
; #define ROPE_LOAD(C0, C1, S0, S1, r_) do { const int pos_ = (u.pm * BM + ((r_) >> 2) * HALF + wr * 64 + ((r_) & 3) * 16 + fr) & (SEQ - 1); const float* cp_ = cosT + pos_ * 32 + fq * 8; const float* sp_ = sinT + pos_ * 32 + fq * 8; \
;             C0 = *(const f32x4*)cp_; C1 = *(const f32x4*)(cp_ + 4); S0 = *(const f32x4*)sp_; S1 = *(const f32x4*)(sp_ + 4); } while (0)
;     __device__ __forceinline__ void operator()(const f32x4 (&acc)[2][2][4][2], const Unit& u, int wr, int wc, int fr, int fq) const {
;     ...
;         EPI_ROWS { rsv[ai][m] = rstd_lds(scr, EPI_LROW); asm volatile("" : "+v"(rsv[ai][m]) :: "memory"); }
;     ...
; #pragma unroll
;         for (int r = 0; r < 8; ++r) { const int ai = r >> 2, m = r & 3; const int row = EPI_ROW; const float rs = rsv[ai][m];
;             f32x4 a0 = acc[ai][0][m][0] * rs + ba0, a1 = acc[ai][0][m][1] * rs + ba1, b0 = acc[ai][1][m][0] * rs + bb0, b1 = acc[ai][1][m][1] * rs + bb1;
;             bf16_t* rp = dst + (size_t)row * pitch;
;             if (mode == 1) { *(u32x4*)(rp + c0) = pack8(a0 * b0, a1 * b1); }
;             else if (mode == 3) {
; #pragma unroll
;                 for (int i = 0; i < 4; ++i) {
;                     const float ea0 = __expf(-a0[i]), ea1 = __expf(-a1[i]), eb0 = __expf(-b0[i]), eb1 = __expf(-b1[i]);
;                     a0[i] = (1.f + eb0) * __builtin_amdgcn_rcpf(1.f + ea0); a1[i] = (1.f + eb1) * __builtin_amdgcn_rcpf(1.f + ea1); b0[i] = __builtin_amdgcn_rcpf(1.f + eb0); b1[i] = __builtin_amdgcn_rcpf(1.f + eb1); }
;                 { const size_t po = (size_t)(row >> 1) * (2 * DM) + ((pn - 18) * 4 + wc) * 64 + (row & 1) * 32 + fq * 8;
;                   *(u32x4*)(SZC + po) = pack8(a0, a1); *(u32x4*)(SZA + po) = pack8(b0, b1); } }
;             else {
;                 if (mode == 2) { f32x4 cA, cB, sA, sB; ROPE_LOAD(cA, cB, sA, sB, r); const f32x4 x0 = a0, x1 = a1, y0 = b0, y1 = b1;
;                     a0 = x0 * cA - y0 * sA; a1 = x1 * cB - y1 * sB; b0 = y0 * cA + x0 * sA; b1 = y1 * cB + x1 * sB; }
	v_pk_add_f32 v[150:151], v[150:151], v[154:155]
	v_pk_add_f32 v[148:149], v[148:149], v[152:153]
	v_pk_add_f32 v[152:153], v[158:159], v[162:163]
	v_pk_add_f32 v[154:155], v[156:157], v[160:161]
	v_pk_add_f32 v[150:151], v[150:151], v[152:153]
	v_pk_add_f32 v[148:149], v[148:149], v[154:155]
	v_add_f32_e32 v148, v148, v149
	v_add_f32_e32 v149, v150, v151
	v_add_f32_e32 v148, v148, v149
	v_fmamk_f32 v148, v148, 0x3a800000, v211
	v_rsq_f32_e32 v176, v148
	v_ashrrev_i32_e32 v165, 31, v164
	s_and_b64 vcc, exec, s[56:57]
	s_waitcnt lgkmcnt(0)
	v_pk_add_f32 v[232:233], v[232:233], v[236:237]
	v_pk_add_f32 v[230:231], v[230:231], v[234:235]
	v_pk_add_f32 v[234:235], v[240:241], v[244:245]
	v_pk_add_f32 v[236:237], v[238:239], v[242:243]
	v_pk_add_f32 v[232:233], v[232:233], v[234:235]
	v_pk_add_f32 v[230:231], v[230:231], v[236:237]
	s_nop 0
	v_add_f32_e32 v230, v230, v231
	v_add_f32_e32 v231, v232, v233
	v_add_f32_e32 v230, v230, v231
	v_fmamk_f32 v230, v230, 0x3a800000, v211
	v_rsq_f32_e32 v174, v230
	v_sub_u32_e32 v148, v204, v164
	v_lshlrev_b32_e32 v150, 7, v175
	v_ashrrev_i32_e32 v149, 31, v148
	v_and_b32_e32 v199, 0x380, v150
	v_lshlrev_b32_e32 v150, 4, v175
	v_lshl_add_u64 v[148:149], v[148:149], 1, s[10:11]
	v_and_b32_e32 v186, 0x70, v150
	v_lshl_add_u64 v[170:171], v[148:149], 0, v[186:187]
	v_ashrrev_i32_e32 v148, 31, v147
	v_mul_lo_u32 v148, s52, v148
	v_mul_lo_u32 v149, s53, v147
	v_add3_u32 v173, v173, v148, v149
	v_and_b32_e32 v148, -8, v175
	v_add_u32_e32 v147, 8, v147
	v_cmp_eq_u32_e64 s[4:5], 8, v148
	v_ashrrev_i32_e32 v148, 31, v147
	v_mul_lo_u32 v148, s52, v148
	v_mul_lo_u32 v149, s53, v147
	v_mad_u64_u32 v[168:169], s[28:29], s52, v147, 0
	v_lshlrev_b32_e32 v147, 5, v175
	v_add3_u32 v169, v169, v148, v149
	v_and_b32_e32 v186, 32, v147
	v_lshl_add_u64 v[148:149], v[164:165], 0, s[8:9]
	v_lshl_add_u64 v[166:167], v[148:149], 0, v[186:187]
	v_pk_fma_f32 v[144:145], v[144:145], v[146:147], v[56:57] op_sel_hi:[1,0,1]
	v_pk_fma_f32 v[142:143], v[142:143], v[146:147], v[54:55] op_sel_hi:[1,0,1]
	v_pk_fma_f32 v[140:141], v[140:141], v[146:147], v[52:53] op_sel_hi:[1,0,1]
	v_pk_fma_f32 v[138:139], v[138:139], v[146:147], v[50:51] op_sel_hi:[1,0,1]
	v_pk_fma_f32 v[136:137], v[136:137], v[146:147], v[48:49] op_sel_hi:[1,0,1]
	v_pk_fma_f32 v[134:135], v[134:135], v[146:147], v[46:47] op_sel_hi:[1,0,1]
	v_pk_fma_f32 v[132:133], v[132:133], v[146:147], v[44:45] op_sel_hi:[1,0,1]
	v_pk_fma_f32 v[130:131], v[130:131], v[146:147], v[42:43] op_sel_hi:[1,0,1]
	s_cbranch_vccz .LBB0_474
	s_mov_b64 s[8:9], -1
	s_and_b64 vcc, exec, s[58:59]
	s_cbranch_vccz .LBB0_471
	v_mov_b64_e32 v[154:155], v[132:133]
	v_mov_b64_e32 v[158:159], v[136:137]
	v_mov_b64_e32 v[150:151], v[140:141]
	v_mov_b64_e32 v[162:163], v[144:145]
	s_andn2_b64 vcc, exec, s[54:55]
	v_mov_b64_e32 v[152:153], v[130:131]
	v_mov_b64_e32 v[156:157], v[134:135]
	v_mov_b64_e32 v[148:149], v[138:139]
	v_mov_b64_e32 v[160:161], v[142:143]
	s_cbranch_vccnz .LBB0_466
	v_lshlrev_b32_e32 v146, 7, v212
	v_and_b32_e32 v186, 0xfff80, v146
	v_lshlrev_b64 v[154:155], 2, v[164:165]
	v_lshl_add_u64 v[146:147], s[20:21], 0, v[186:187]
	v_lshl_add_u64 v[150:151], v[146:147], 0, v[154:155]
	v_lshl_add_u64 v[156:157], s[18:19], 0, v[186:187]
	global_load_dwordx4 v[146:149], v[150:151], off
	s_nop 0
	global_load_dwordx4 v[150:153], v[150:151], off offset:16
	v_lshl_add_u64 v[158:159], v[156:157], 0, v[154:155]
	global_load_dwordx4 v[154:157], v[158:159], off
	global_load_dwordx4 v[214:217], v[158:159], off offset:16
	s_waitcnt vmcnt(0)
	v_pk_mul_f32 v[158:159], v[136:137], v[148:149]
	v_pk_mul_f32 v[160:161], v[134:135], v[146:147]
	v_pk_mul_f32 v[218:219], v[132:133], v[152:153]
	v_pk_mul_f32 v[222:223], v[130:131], v[150:151]
	v_pk_mul_f32 v[224:225], v[144:145], v[148:149]
	v_pk_mul_f32 v[146:147], v[142:143], v[146:147]
	v_pk_mul_f32 v[152:153], v[140:141], v[152:153]
	v_pk_mul_f32 v[226:227], v[138:139], v[150:151]
	v_pk_fma_f32 v[162:163], v[144:145], v[156:157], v[158:159] neg_lo:[0,0,1] neg_hi:[0,0,1]
	v_pk_fma_f32 v[160:161], v[142:143], v[154:155], v[160:161] neg_lo:[0,0,1] neg_hi:[0,0,1]
	v_pk_fma_f32 v[150:151], v[140:141], v[216:217], v[218:219] neg_lo:[0,0,1] neg_hi:[0,0,1]
	v_pk_fma_f32 v[148:149], v[138:139], v[214:215], v[222:223] neg_lo:[0,0,1] neg_hi:[0,0,1]
	v_pk_fma_f32 v[158:159], v[136:137], v[156:157], v[224:225]
	v_pk_fma_f32 v[156:157], v[134:135], v[154:155], v[146:147]
	v_pk_fma_f32 v[154:155], v[132:133], v[216:217], v[152:153]
	v_pk_fma_f32 v[152:153], v[130:131], v[214:215], v[226:227]

; template <class Epi, class Sched, bool ALIGN_EPI = false, bool SP2 = false>
; __device__ __forceinline__ void gemm_phase(PG8_LAS unsigned char* lds, const Gemm g, const Sched& S, const Epi& E) {
;     ...
;         for (int a = 0; a < 2; ++a)
; #pragma unroll
;             for (int b = 0; b < 2; ++b)
; #pragma unroll
;                 for (int m = 0; m < 4; ++m)
; #pragma unroll
;                     for (int n = 0; n < 2; ++n) acc[a][b][m][n] = (f32x4){0.f, 0.f, 0.f, 0.f};
;         cur = nxt; cA = nA; cB = nB; ++ui;
.LBB0_837:
	s_ashr_i32 s29, s28, 31
	s_lshl_b64 s[30:31], s[28:29], 19
	s_add_u32 s30, s46, s30
	s_addc_u32 s31, s47, s31
	s_and_b64 s[34:35], s[2:3], exec
	s_cselect_b32 s1, s31, s5
	s_cselect_b32 s29, s30, s4
	s_ashr_i32 s27, s26, 31
	s_lshl_b64 s[34:35], s[26:27], 19
	s_add_u32 s34, s48, s34
	s_addc_u32 s35, s49, s35
	s_and_b64 s[36:37], s[2:3], exec
	s_cselect_b32 s27, s35, s7
	s_cselect_b32 s38, s34, s6
	s_add_u32 s4, s4, 0x40080
	s_addc_u32 s5, s5, 0
	s_add_u32 s39, s6, 0x100
	s_addc_u32 s40, s7, 0
	s_mov_b32 s41, -2
	s_waitcnt lgkmcnt(0)
	v_mov_b64_e32 v[2:3], 0
	v_mov_b64_e32 v[4:5], 0
	v_mov_b64_e32 v[6:7], 0
	v_mov_b64_e32 v[8:9], 0
	v_mov_b64_e32 v[10:11], 0
	v_mov_b64_e32 v[12:13], 0
	v_mov_b64_e32 v[14:15], 0
	v_mov_b64_e32 v[16:17], 0
	v_mov_b64_e32 v[18:19], 0
	v_mov_b64_e32 v[20:21], 0
	v_mov_b64_e32 v[22:23], 0
	v_mov_b64_e32 v[24:25], 0
	v_mov_b64_e32 v[26:27], 0
	v_mov_b64_e32 v[28:29], 0
	v_mov_b64_e32 v[30:31], 0
	v_mov_b64_e32 v[32:33], 0
	v_mov_b64_e32 v[34:35], 0
	v_mov_b64_e32 v[36:37], 0
	v_mov_b64_e32 v[38:39], 0
	v_mov_b64_e32 v[40:41], 0
	v_mov_b64_e32 v[42:43], 0
	v_mov_b64_e32 v[44:45], 0
	v_mov_b64_e32 v[46:47], 0
	v_mov_b64_e32 v[48:49], 0
	v_mov_b64_e32 v[58:59], 0
	v_mov_b64_e32 v[60:61], 0
	v_mov_b64_e32 v[62:63], 0
	v_mov_b64_e32 v[64:65], 0
	v_mov_b64_e32 v[74:75], 0
	v_mov_b64_e32 v[76:77], 0
	v_mov_b64_e32 v[78:79], 0
	v_mov_b64_e32 v[80:81], 0
	v_mov_b64_e32 v[82:83], 0
	v_mov_b64_e32 v[84:85], 0
	v_mov_b64_e32 v[86:87], 0
	v_mov_b64_e32 v[88:89], 0
	v_mov_b64_e32 v[90:91], 0
	v_mov_b64_e32 v[92:93], 0
	v_mov_b64_e32 v[94:95], 0
	v_mov_b64_e32 v[96:97], 0
	v_mov_b64_e32 v[98:99], 0
	v_mov_b64_e32 v[100:101], 0
	v_mov_b64_e32 v[102:103], 0
	v_mov_b64_e32 v[104:105], 0
	v_mov_b64_e32 v[106:107], 0
	v_mov_b64_e32 v[108:109], 0
	v_mov_b64_e32 v[110:111], 0
	v_mov_b64_e32 v[112:113], 0
	v_mov_b64_e32 v[114:115], 0
	v_mov_b64_e32 v[116:117], 0
	v_mov_b64_e32 v[118:119], 0
	v_mov_b64_e32 v[120:121], 0
	v_mov_b64_e32 v[122:123], 0
	v_mov_b64_e32 v[124:125], 0
	v_mov_b64_e32 v[126:127], 0
	v_mov_b64_e32 v[128:129], 0
	v_mov_b64_e32 v[130:131], 0
	v_mov_b64_e32 v[132:133], 0
	v_mov_b64_e32 v[134:135], 0
	v_mov_b64_e32 v[136:137], 0
	v_mov_b64_e32 v[138:139], 0
	v_mov_b64_e32 v[140:141], 0
	v_mov_b64_e32 v[142:143], 0
	v_mov_b64_e32 v[144:145], 0

; template <class Epi, class Sched, bool ALIGN_EPI = false, bool SP2 = false>
; __device__ __forceinline__ void gemm_phase(PG8_LAS unsigned char* lds, const Gemm g, const Sched& S, const Epi& E) {
;     ...
;         for (int a = 0; a < 2; ++a)
; #pragma unroll
;             for (int b = 0; b < 2; ++b)
; #pragma unroll
;                 for (int m = 0; m < 4; ++m)
; #pragma unroll
;                     for (int n = 0; n < 2; ++n) acc[a][b][m][n] = (f32x4){0.f, 0.f, 0.f, 0.f};
;         cur = nxt; cA = nA; cB = nB; ++ui;
.LBB0_984:
	s_ashr_i32 s23, s22, 31
	s_lshl_b64 s[24:25], s[22:23], 19
	s_add_u32 s24, s47, s24
	s_addc_u32 s25, s48, s25
	s_and_b64 s[26:27], s[2:3], exec
	s_cselect_b32 s23, s25, s31
	s_cselect_b32 s81, s24, s30
	s_ashr_i32 s21, s20, 31
	s_lshl_b64 s[26:27], s[20:21], 19
	s_add_u32 s26, s49, s26
	s_addc_u32 s27, s50, s27
	s_and_b64 s[36:37], s[2:3], exec
	s_cselect_b32 s21, s27, s41
	s_cselect_b32 s82, s26, s40
	s_ashr_i32 s29, s28, 31
	s_lshl_b32 s34, s34, 8
	s_lshl_b64 s[36:37], s[28:29], 14
	s_ashr_i32 s29, s28, 5
	s_ashr_i32 s35, s34, 31
	s_add_u32 s36, s10, s36
	s_mul_hi_i32 s38, s29, 0x5800
	s_mulk_i32 s29, 0x5800
	s_addc_u32 s37, s69, s37
	s_add_u32 s29, s62, s29
	s_addc_u32 s42, s63, s38
	s_lshl_b64 s[38:39], s[34:35], 2
	s_add_u32 s38, s29, s38
	s_addc_u32 s39, s42, s39
	s_add_u32 s29, s40, 0x100
	v_lshl_add_u64 v[188:189], s[30:31], 0, v[180:181]
	v_lshl_add_u64 v[190:191], s[30:31], 0, v[182:183]
	s_addc_u32 s35, s41, 0
	s_mov_b32 s83, 0
	s_mov_b64 s[40:41], 0
	v_mov_b64_e32 v[2:3], 0
	v_mov_b64_e32 v[4:5], 0
	v_mov_b64_e32 v[6:7], 0
	v_mov_b64_e32 v[8:9], 0
	v_mov_b64_e32 v[10:11], 0
	v_mov_b64_e32 v[12:13], 0
	v_mov_b64_e32 v[14:15], 0
	v_mov_b64_e32 v[16:17], 0
	v_mov_b64_e32 v[18:19], 0
	v_mov_b64_e32 v[20:21], 0
	v_mov_b64_e32 v[22:23], 0
	v_mov_b64_e32 v[24:25], 0
	v_mov_b64_e32 v[26:27], 0
	v_mov_b64_e32 v[28:29], 0
	v_mov_b64_e32 v[30:31], 0
	v_mov_b64_e32 v[32:33], 0
	v_mov_b64_e32 v[34:35], 0
	v_mov_b64_e32 v[36:37], 0
	v_mov_b64_e32 v[38:39], 0
	v_mov_b64_e32 v[40:41], 0
	v_mov_b64_e32 v[42:43], 0
	v_mov_b64_e32 v[44:45], 0
	v_mov_b64_e32 v[46:47], 0
	v_mov_b64_e32 v[48:49], 0
	v_mov_b64_e32 v[50:51], 0
	v_mov_b64_e32 v[52:53], 0
	v_mov_b64_e32 v[54:55], 0
	v_mov_b64_e32 v[56:57], 0
	v_mov_b64_e32 v[58:59], 0
	v_mov_b64_e32 v[60:61], 0
	v_mov_b64_e32 v[62:63], 0
	v_mov_b64_e32 v[64:65], 0
	v_mov_b64_e32 v[66:67], 0
	v_mov_b64_e32 v[68:69], 0
	v_mov_b64_e32 v[70:71], 0
	v_mov_b64_e32 v[72:73], 0
	v_mov_b64_e32 v[74:75], 0
	v_mov_b64_e32 v[76:77], 0
	v_mov_b64_e32 v[78:79], 0
	v_mov_b64_e32 v[80:81], 0
	v_mov_b64_e32 v[82:83], 0
	v_mov_b64_e32 v[84:85], 0
	v_mov_b64_e32 v[86:87], 0
	v_mov_b64_e32 v[88:89], 0
	v_mov_b64_e32 v[90:91], 0
	v_mov_b64_e32 v[92:93], 0
	v_mov_b64_e32 v[94:95], 0
	v_mov_b64_e32 v[96:97], 0
	v_mov_b64_e32 v[102:103], 0
	v_mov_b64_e32 v[104:105], 0
	v_mov_b64_e32 v[110:111], 0
	v_mov_b64_e32 v[112:113], 0
	v_mov_b64_e32 v[114:115], 0
	v_mov_b64_e32 v[116:117], 0
	v_mov_b64_e32 v[118:119], 0
	v_mov_b64_e32 v[120:121], 0
	v_mov_b64_e32 v[122:123], 0
	v_mov_b64_e32 v[124:125], 0
	v_mov_b64_e32 v[126:127], 0
	v_mov_b64_e32 v[128:129], 0
	v_mov_b64_e32 v[130:131], 0
	v_mov_b64_e32 v[132:133], 0
	v_mov_b64_e32 v[134:135], 0
	v_mov_b64_e32 v[136:137], 0
	s_branch .LBB0_986

; template <class Epi, class Sched, bool ALIGN_EPI = false, bool SP2 = false>
; __device__ __forceinline__ void gemm_phase(PG8_LAS unsigned char* lds, const Gemm g, const Sched& S, const Epi& E) {
;     ...
;         for (int a = 0; a < 2; ++a)
; #pragma unroll
;             for (int b = 0; b < 2; ++b)
; #pragma unroll
;                 for (int m = 0; m < 4; ++m)
; #pragma unroll
;                     for (int n = 0; n < 2; ++n) acc[a][b][m][n] = (f32x4){0.f, 0.f, 0.f, 0.f};
;         cur = nxt; cA = nA; cB = nB; ++ui;
.LBB0_1068:
	s_add_u32 s35, s6, 0x100
	s_addc_u32 s36, s7, 0
	s_mov_b32 s37, -2
	s_waitcnt lgkmcnt(0)
	v_mov_b64_e32 v[2:3], 0
	v_mov_b64_e32 v[4:5], 0
	v_mov_b64_e32 v[6:7], 0
	v_mov_b64_e32 v[8:9], 0
	v_mov_b64_e32 v[10:11], 0
	v_mov_b64_e32 v[12:13], 0
	v_mov_b64_e32 v[14:15], 0
	v_mov_b64_e32 v[16:17], 0
	v_mov_b64_e32 v[18:19], 0
	v_mov_b64_e32 v[20:21], 0
	v_mov_b64_e32 v[22:23], 0
	v_mov_b64_e32 v[24:25], 0
	v_mov_b64_e32 v[26:27], 0
	v_mov_b64_e32 v[28:29], 0
	v_mov_b64_e32 v[30:31], 0
	v_mov_b64_e32 v[32:33], 0
	v_mov_b64_e32 v[34:35], 0
	v_mov_b64_e32 v[36:37], 0
	v_mov_b64_e32 v[38:39], 0
	v_mov_b64_e32 v[40:41], 0
	v_mov_b64_e32 v[42:43], 0
	v_mov_b64_e32 v[44:45], 0
	v_mov_b64_e32 v[46:47], 0
	v_mov_b64_e32 v[48:49], 0
	v_mov_b64_e32 v[50:51], 0
	v_mov_b64_e32 v[52:53], 0
	v_mov_b64_e32 v[54:55], 0
	v_mov_b64_e32 v[56:57], 0
	v_mov_b64_e32 v[58:59], 0
	v_mov_b64_e32 v[60:61], 0
	v_mov_b64_e32 v[62:63], 0
	v_mov_b64_e32 v[64:65], 0
	v_mov_b64_e32 v[66:67], 0
	v_mov_b64_e32 v[68:69], 0
	v_mov_b64_e32 v[70:71], 0
	v_mov_b64_e32 v[72:73], 0
	v_mov_b64_e32 v[74:75], 0
	v_mov_b64_e32 v[76:77], 0
	v_mov_b64_e32 v[78:79], 0
	v_mov_b64_e32 v[80:81], 0
	v_mov_b64_e32 v[82:83], 0
	v_mov_b64_e32 v[84:85], 0
	v_mov_b64_e32 v[86:87], 0
	v_mov_b64_e32 v[88:89], 0
	v_mov_b64_e32 v[90:91], 0
	v_mov_b64_e32 v[92:93], 0
	v_mov_b64_e32 v[94:95], 0
	v_mov_b64_e32 v[96:97], 0
	v_mov_b64_e32 v[98:99], 0
	v_mov_b64_e32 v[100:101], 0
	v_mov_b64_e32 v[102:103], 0
	v_mov_b64_e32 v[104:105], 0
	v_mov_b64_e32 v[106:107], 0
	v_mov_b64_e32 v[108:109], 0
	v_mov_b64_e32 v[110:111], 0
	v_mov_b64_e32 v[112:113], 0
	v_mov_b64_e32 v[114:115], 0
	v_mov_b64_e32 v[116:117], 0
	v_mov_b64_e32 v[118:119], 0
	v_mov_b64_e32 v[120:121], 0
	v_mov_b64_e32 v[122:123], 0
	v_mov_b64_e32 v[124:125], 0
	v_mov_b64_e32 v[126:127], 0
	v_mov_b64_e32 v[128:129], 0
